# the xor-1/2/4/8 hops of the ds_bpermute butterfly sums in norm_rows, sg_stats and the sg_mix position-weight row sums replaced by DPP row adds (bit-identical sums, no LDS round trip per hop); on top o
# speedup vs baseline: 1.0156x; 1.0021x over previous
; DI unsigned pk2(float lo, float hi) { return pg8::cvt_pk_bf16(lo, hi); }
; DI float wave_sum(float v) {
; #pragma unroll
;     for (int o = 1; o < 64; o <<= 1) v += __shfl_xor(v, o);
;     return v;
; }
; DI void norm_rows(const float* X, const float* gain, const float* sh, const float* sc, bf16_t* H, int gw, int ngw, int lane) {
;     ...
;         const f32x4* xr = (const f32x4*)(X + (size_t)m * DM) + lane;
;         f32x4 v[8]; float s = 0.f;
; #pragma unroll
;         for (int j = 0; j < 8; ++j) { v[j] = xr[64 * j]; s += (v[j].x * v[j].x + v[j].y * v[j].y) + (v[j].z * v[j].z + v[j].w * v[j].w); }
;         const float rstd = rsqrtf(wave_sum(s) * (1.f / DM) + EPS);
;         const f32x4* gp = (const f32x4*)gain + lane; const f32x4* scp = (const f32x4*)(sc + (size_t)b * MODW) + lane; const f32x4* shp = (const f32x4*)(sh + (size_t)b * MODW) + lane;
;         u32x2* o = (u32x2*)(H + (size_t)m * DM) + lane;
; #pragma unroll
;         for (int j = 0; j < 8; ++j) { const f32x4 r = v[j] * rstd * gp[64 * j] * (scp[64 * j] + 1.0f) + shp[64 * j]; u32x2 w; w.x = pk2(r.x, r.y); w.y = pk2(r.z, r.w); o[64 * j] = w; }
.LBB0_158:
	global_load_dwordx4 v[28:31], v[46:47], off offset:-4096
	global_load_dwordx4 v[24:27], v[46:47], off offset:-3072
	global_load_dwordx4 v[20:23], v[46:47], off offset:-2048
	global_load_dwordx4 v[4:7], v[46:47], off offset:1024
	global_load_dwordx4 v[12:15], v[46:47], off offset:-1024
	global_load_dwordx4 v[16:19], v[46:47], off
	global_load_dwordx4 v[8:11], v[46:47], off offset:2048
	global_load_dwordx4 v[0:3], v[46:47], off offset:3072
	global_load_dwordx4 v[58:61], v[32:33], off
	s_ashr_i32 s12, s4, 12
	v_mad_i64_i32 v[70:71], s[10:11], s12, v57, v[34:35]
	v_mad_i64_i32 v[72:73], s[10:11], s12, v57, v[36:37]
	global_load_dwordx4 v[62:65], v[70:71], off
	global_load_dwordx4 v[66:69], v[72:73], off
	v_lshl_add_u64 v[108:109], v[70:71], 0, s[98:99]
	v_lshl_add_u64 v[110:111], v[72:73], 0, s[98:99]
	global_load_dwordx4 v[112:115], v[32:33], off offset:1024
	global_load_dwordx4 v[116:119], v[70:71], off offset:1024
	global_load_dwordx4 v[120:123], v[72:73], off offset:1024
	global_load_dwordx4 v[124:127], v[32:33], off offset:2048
	global_load_dwordx4 v[128:131], v[70:71], off offset:2048
	global_load_dwordx4 v[132:135], v[72:73], off offset:2048
	global_load_dwordx4 v[136:139], v[32:33], off offset:3072
	global_load_dwordx4 v[140:143], v[70:71], off offset:3072
	global_load_dwordx4 v[148:151], v[72:73], off offset:3072
	global_load_dwordx4 v[152:155], v[38:39], off
	global_load_dwordx4 v[156:159], v[108:109], off
	global_load_dwordx4 v[160:163], v[110:111], off
	global_load_dwordx4 v[164:167], v[40:41], off
	global_load_dwordx4 v[168:171], v[108:109], off offset:1024
	global_load_dwordx4 v[172:175], v[110:111], off offset:1024
	global_load_dwordx4 v[176:179], v[42:43], off
	global_load_dwordx4 v[180:183], v[108:109], off offset:2048
	global_load_dwordx4 v[184:187], v[110:111], off offset:2048
	global_load_dwordx4 v[188:191], v[44:45], off
	global_load_dwordx4 v[192:195], v[108:109], off offset:3072
	global_load_dwordx4 v[196:199], v[110:111], off offset:3072
	s_add_i32 s4, s4, s84
	v_lshl_add_u64 v[46:47], v[46:47], 0, s[6:7]
	s_cmpk_lt_i32 s4, 0x4000
	s_waitcnt vmcnt(31)
	v_mov_b32_e32 v76, v29
	s_waitcnt vmcnt(30)
	v_mov_b32_e32 v77, v25
	s_waitcnt vmcnt(29)
	v_pk_mul_f32 v[78:79], v[22:23], v[22:23]
	v_pk_mul_f32 v[80:81], v[20:21], v[20:21]
	s_waitcnt vmcnt(28)
	v_pk_mul_f32 v[82:83], v[6:7], v[6:7]
	v_pk_mul_f32 v[84:85], v[4:5], v[4:5]
	v_mov_b32_e32 v88, v31
	v_mov_b32_e32 v89, v27
	v_mov_b32_e32 v74, v28
	v_mov_b32_e32 v75, v24
	v_mov_b32_e32 v86, v30
	v_mov_b32_e32 v87, v26
	v_pk_mov_b32 v[98:99], v[80:81], v[78:79] op_sel:[1,0]
	v_mov_b32_e32 v81, v79
	v_pk_mov_b32 v[78:79], v[84:85], v[82:83] op_sel:[1,0]
	v_mov_b32_e32 v85, v83
	v_pk_mul_f32 v[76:77], v[76:77], v[76:77]
	v_pk_mul_f32 v[82:83], v[88:89], v[88:89]
	v_pk_fma_f32 v[74:75], v[74:75], v[74:75], v[76:77]
	v_pk_fma_f32 v[76:77], v[86:87], v[86:87], v[82:83]
	s_waitcnt vmcnt(27)
	v_mul_f32_e32 v90, v13, v13
	v_mul_f32_e32 v92, v15, v15
	v_pk_add_f32 v[80:81], v[98:99], v[80:81]
	v_pk_add_f32 v[74:75], v[74:75], v[76:77]
	s_waitcnt vmcnt(26)
	v_mul_f32_e32 v97, v18, v18
	v_mul_f32_e32 v100, v19, v19
	v_mul_f32_e32 v103, v17, v17
	v_mul_f32_e32 v104, v16, v16
	v_pk_fma_f32 v[88:89], v[12:13], v[12:13], v[90:91] op_sel_hi:[1,1,0]
	v_pk_fma_f32 v[90:91], v[14:15], v[14:15], v[92:93] op_sel_hi:[1,1,0]
	v_pk_add_f32 v[80:81], v[80:81], v[80:81] op_sel:[0,1] op_sel_hi:[1,0]
	v_pk_add_f32 v[74:75], v[74:75], v[74:75] op_sel:[0,1] op_sel_hi:[1,0]
	v_mov_b32_e32 v89, v97
	v_mov_b32_e32 v91, v100
	v_mov_b32_e32 v81, v103
	v_mov_b32_e32 v75, v104
	v_pk_add_f32 v[76:77], v[88:89], v[90:91]
	v_pk_add_f32 v[74:75], v[74:75], v[80:81]
	s_waitcnt vmcnt(25)
	v_mul_f32_e32 v94, v9, v9
	v_mul_f32_e32 v96, v11, v11
	v_pk_add_f32 v[78:79], v[78:79], v[84:85]
	v_pk_add_f32 v[74:75], v[74:75], v[76:77]
	s_waitcnt vmcnt(24)
	v_mul_f32_e32 v101, v2, v2
	v_mul_f32_e32 v102, v3, v3
	v_mul_f32_e32 v105, v1, v1
	v_mul_f32_e32 v106, v0, v0
	v_pk_fma_f32 v[92:93], v[8:9], v[8:9], v[94:95] op_sel_hi:[1,1,0]
	v_pk_fma_f32 v[94:95], v[10:11], v[10:11], v[96:97] op_sel_hi:[1,1,0]
	v_pk_add_f32 v[78:79], v[78:79], v[78:79] op_sel:[0,1] op_sel_hi:[1,0]
	v_pk_add_f32 v[74:75], v[74:75], v[74:75] op_sel:[0,1] op_sel_hi:[1,0]
	v_mov_b32_e32 v93, v101
	v_mov_b32_e32 v95, v102
	v_mov_b32_e32 v79, v105
	v_mov_b32_e32 v75, v106
	v_pk_add_f32 v[82:83], v[92:93], v[94:95]
	v_pk_add_f32 v[74:75], v[74:75], v[78:79]
	s_waitcnt vmcnt(22)
	v_pk_add_f32 v[64:65], v[64:65], 1.0 op_sel_hi:[1,0]
	v_pk_add_f32 v[74:75], v[74:75], v[82:83]
	v_pk_add_f32 v[62:63], v[62:63], 1.0 op_sel_hi:[1,0]
	v_add_f32_e32 v74, v74, v75
	s_waitcnt lgkmcnt(0)
	s_nop 1
	v_add_f32_dpp v74, v74, v74 quad_perm:[1,0,3,2] row_mask:0xf bank_mask:0xf
	s_waitcnt lgkmcnt(0)
	s_nop 1
	v_add_f32_dpp v74, v74, v74 quad_perm:[2,3,0,1] row_mask:0xf bank_mask:0xf
	s_waitcnt lgkmcnt(0)
	s_nop 1
	v_add_f32_dpp v74, v74, v74 row_half_mirror row_mask:0xf bank_mask:0xf
	s_waitcnt lgkmcnt(0)
	s_nop 1
	v_add_f32_dpp v74, v74, v74 row_mirror row_mask:0xf bank_mask:0xf
	ds_bpermute_b32 v75, v54, v74
	s_waitcnt lgkmcnt(0)
	v_add_f32_e32 v74, v74, v75
	ds_bpermute_b32 v75, v55, v74
	s_waitcnt lgkmcnt(0)
; DI unsigned pk2(float lo, float hi) { return pg8::cvt_pk_bf16(lo, hi); }
; DI void norm_rows(const float* X, const float* gain, const float* sh, const float* sc, bf16_t* H, int gw, int ngw, int lane) {
;     ...
;         const float rstd = rsqrtf(wave_sum(s) * (1.f / DM) + EPS);
;         const f32x4* gp = (const f32x4*)gain + lane; const f32x4* scp = (const f32x4*)(sc + (size_t)b * MODW) + lane; const f32x4* shp = (const f32x4*)(sh + (size_t)b * MODW) + lane;
;         u32x2* o = (u32x2*)(H + (size_t)m * DM) + lane;
; #pragma unroll
;         for (int j = 0; j < 8; ++j) { const f32x4 r = v[j] * rstd * gp[64 * j] * (scp[64 * j] + 1.0f) + shp[64 * j]; u32x2 w; w.x = pk2(r.x, r.y); w.y = pk2(r.z, r.w); o[64 * j] = w; }
	v_add_f32_e32 v74, v74, v75
	v_fmamk_f32 v74, v74, 0x3a000000, v56
	v_mul_f32_e32 v75, 0x4b800000, v74
	v_cmp_gt_f32_e32 vcc, s3, v74
	s_nop 1
	v_cndmask_b32_e32 v74, v74, v75, vcc
	v_rsq_f32_e32 v74, v74
	s_nop 0
	v_mul_f32_e32 v75, 0x45800000, v74
	v_cndmask_b32_e32 v74, v74, v75, vcc
	v_pk_mul_f32 v[30:31], v[30:31], v[74:75] op_sel_hi:[1,0]
	v_pk_mul_f32 v[28:29], v[28:29], v[74:75] op_sel_hi:[1,0]
	v_pk_mul_f32 v[30:31], v[60:61], v[30:31]
	v_pk_mul_f32 v[28:29], v[58:59], v[28:29]
	s_waitcnt vmcnt(21)
	v_pk_fma_f32 v[30:31], v[64:65], v[30:31], v[68:69]
	v_pk_fma_f32 v[28:29], v[62:63], v[28:29], v[66:67]
	v_pk_mul_f32 v[26:27], v[26:27], v[74:75] op_sel_hi:[1,0]
	v_cvt_pk_bf16_f32 v28, v28, v29
	v_cvt_pk_bf16_f32 v29, v30, v31
	global_store_dwordx2 v[48:49], v[28:29], off
	v_pk_mul_f32 v[24:25], v[24:25], v[74:75] op_sel_hi:[1,0]
	v_pk_mul_f32 v[22:23], v[22:23], v[74:75] op_sel_hi:[1,0]
	v_pk_mul_f32 v[20:21], v[20:21], v[74:75] op_sel_hi:[1,0]
	v_pk_mul_f32 v[14:15], v[14:15], v[74:75] op_sel_hi:[1,0]
	v_pk_mul_f32 v[12:13], v[12:13], v[74:75] op_sel_hi:[1,0]
	v_pk_mul_f32 v[18:19], v[18:19], v[74:75] op_sel_hi:[1,0]
	v_pk_mul_f32 v[16:17], v[16:17], v[74:75] op_sel_hi:[1,0]
	v_pk_mul_f32 v[6:7], v[6:7], v[74:75] op_sel_hi:[1,0]
	v_pk_mul_f32 v[4:5], v[4:5], v[74:75] op_sel_hi:[1,0]
	v_pk_mul_f32 v[10:11], v[10:11], v[74:75] op_sel_hi:[1,0]
	v_pk_mul_f32 v[8:9], v[8:9], v[74:75] op_sel_hi:[1,0]
	v_pk_mul_f32 v[2:3], v[2:3], v[74:75] op_sel_hi:[1,0]
	v_pk_mul_f32 v[0:1], v[0:1], v[74:75] op_sel_hi:[1,0]
	s_waitcnt vmcnt(20)
	v_pk_mul_f32 v[24:25], v[112:113], v[24:25]
	v_pk_mul_f32 v[26:27], v[114:115], v[26:27]
	s_waitcnt vmcnt(19)
	v_pk_add_f32 v[28:29], v[118:119], 1.0 op_sel_hi:[1,0]
	v_pk_add_f32 v[30:31], v[116:117], 1.0 op_sel_hi:[1,0]
	s_waitcnt vmcnt(18)
	v_pk_fma_f32 v[26:27], v[28:29], v[26:27], v[122:123]
	v_pk_fma_f32 v[24:25], v[30:31], v[24:25], v[120:121]
	s_nop 0
	v_cvt_pk_bf16_f32 v24, v24, v25
	v_cvt_pk_bf16_f32 v25, v26, v27
	global_store_dwordx2 v[48:49], v[24:25], off offset:512
	s_waitcnt vmcnt(17)
	v_pk_mul_f32 v[20:21], v[124:125], v[20:21]
	v_pk_mul_f32 v[22:23], v[126:127], v[22:23]
	s_waitcnt vmcnt(16)
	v_pk_add_f32 v[24:25], v[130:131], 1.0 op_sel_hi:[1,0]
	v_pk_add_f32 v[26:27], v[128:129], 1.0 op_sel_hi:[1,0]
	s_waitcnt vmcnt(15)
	v_pk_fma_f32 v[22:23], v[24:25], v[22:23], v[134:135]
	v_pk_fma_f32 v[20:21], v[26:27], v[20:21], v[132:133]
	v_add_co_u32_e32 v58, vcc, s5, v70
	v_cvt_pk_bf16_f32 v20, v20, v21
	v_cvt_pk_bf16_f32 v21, v22, v23
	global_store_dwordx2 v[48:49], v[20:21], off offset:1024
	v_addc_co_u32_e32 v59, vcc, 0, v71, vcc
	v_add_co_u32_e32 v60, vcc, s5, v72
	s_waitcnt vmcnt(14)
	v_pk_mul_f32 v[12:13], v[136:137], v[12:13]
	v_pk_mul_f32 v[14:15], v[138:139], v[14:15]
	s_waitcnt vmcnt(13)
	v_pk_add_f32 v[20:21], v[142:143], 1.0 op_sel_hi:[1,0]
	v_pk_add_f32 v[22:23], v[140:141], 1.0 op_sel_hi:[1,0]
	s_waitcnt vmcnt(12)
	v_pk_fma_f32 v[14:15], v[20:21], v[14:15], v[150:151]
	v_pk_fma_f32 v[12:13], v[22:23], v[12:13], v[148:149]
	v_addc_co_u32_e32 v61, vcc, 0, v73, vcc
	v_cvt_pk_bf16_f32 v12, v12, v13
	v_cvt_pk_bf16_f32 v13, v14, v15
	global_store_dwordx2 v[48:49], v[12:13], off offset:1536
	s_waitcnt vmcnt(11)
	v_pk_mul_f32 v[12:13], v[16:17], v[152:153]
	v_pk_mul_f32 v[14:15], v[18:19], v[154:155]
	s_waitcnt vmcnt(10)
	v_pk_add_f32 v[16:17], v[158:159], 1.0 op_sel_hi:[1,0]
	v_pk_add_f32 v[18:19], v[156:157], 1.0 op_sel_hi:[1,0]
	s_waitcnt vmcnt(9)
	v_pk_fma_f32 v[14:15], v[14:15], v[16:17], v[162:163]
	v_pk_fma_f32 v[12:13], v[12:13], v[18:19], v[160:161]
	s_nop 0
	v_cvt_pk_bf16_f32 v12, v12, v13
	v_cvt_pk_bf16_f32 v13, v14, v15
	global_store_dwordx2 v[48:49], v[12:13], off offset:2048
	s_waitcnt vmcnt(8)
	v_pk_mul_f32 v[4:5], v[4:5], v[164:165]
	v_pk_mul_f32 v[6:7], v[6:7], v[166:167]
	s_waitcnt vmcnt(7)
	v_pk_add_f32 v[12:13], v[170:171], 1.0 op_sel_hi:[1,0]
	v_pk_add_f32 v[14:15], v[168:169], 1.0 op_sel_hi:[1,0]
	s_waitcnt vmcnt(6)
	v_pk_fma_f32 v[6:7], v[6:7], v[12:13], v[174:175]
	v_pk_fma_f32 v[4:5], v[4:5], v[14:15], v[172:173]
	s_nop 0
	v_cvt_pk_bf16_f32 v4, v4, v5
	v_cvt_pk_bf16_f32 v5, v6, v7
	global_store_dwordx2 v[48:49], v[4:5], off offset:2560
	s_waitcnt vmcnt(5)
	v_pk_mul_f32 v[4:5], v[8:9], v[176:177]
	v_pk_mul_f32 v[6:7], v[10:11], v[178:179]
	s_waitcnt vmcnt(4)
	v_pk_add_f32 v[8:9], v[182:183], 1.0 op_sel_hi:[1,0]
	v_pk_add_f32 v[10:11], v[180:181], 1.0 op_sel_hi:[1,0]
	s_waitcnt vmcnt(3)
	v_pk_fma_f32 v[6:7], v[6:7], v[8:9], v[186:187]
	v_pk_fma_f32 v[4:5], v[4:5], v[10:11], v[184:185]
	s_nop 0
	v_cvt_pk_bf16_f32 v4, v4, v5
	v_cvt_pk_bf16_f32 v5, v6, v7
	global_store_dwordx2 v[48:49], v[4:5], off offset:3072
	s_waitcnt vmcnt(2)
	v_pk_mul_f32 v[0:1], v[0:1], v[188:189]
	v_pk_mul_f32 v[2:3], v[2:3], v[190:191]
	s_waitcnt vmcnt(1)
	v_pk_add_f32 v[4:5], v[194:195], 1.0 op_sel_hi:[1,0]
	v_pk_add_f32 v[6:7], v[192:193], 1.0 op_sel_hi:[1,0]
	s_waitcnt vmcnt(0)
	v_pk_fma_f32 v[2:3], v[2:3], v[4:5], v[198:199]
	v_pk_fma_f32 v[0:1], v[0:1], v[6:7], v[196:197]
	s_nop 0
	v_cvt_pk_bf16_f32 v0, v0, v1
	v_cvt_pk_bf16_f32 v1, v2, v3
	global_store_dwordx2 v[48:49], v[0:1], off offset:3584
	v_lshl_add_u64 v[48:49], v[48:49], 0, s[8:9]
	s_cbranch_scc1 .LBB0_158

; DI void unpack8(const u32x4 w, float (&f)[8]) { f[0] = bflo(w.x); f[1] = bfhi(w.x); f[2] = bflo(w.y); f[3] = bfhi(w.y); f[4] = bflo(w.z); f[5] = bfhi(w.z); f[6] = bflo(w.w); f[7] = bfhi(w.w); }
; DI void sg_stats(const bf16_t* Z, float* stats, int gw, int ngw, int lane) {
;     for (int m = gw; m < T_TOK; m += ngw) {
;         const u32x4* zr = (const u32x4*)(Z + (size_t)m * 4096 + 2048) + lane;
;         float f[4][8]; float s = 0.f;
; #pragma unroll
;         for (int j = 0; j < 4; ++j) { unpack8(zr[64 * j], f[j]);
; #pragma unroll
;             for (int e = 0; e < 8; ++e) s += f[j][e]; }
;         const float mean = wave_sum(s) * (1.f / 2048.f); float q = 0.f;
; #pragma unroll
;         for (int j = 0; j < 4; ++j)
; #pragma unroll
;             for (int e = 0; e < 8; ++e) { const float dd = f[j][e] - mean; q += dd * dd; }
;         const float rstd = rsqrtf(wave_sum(q) * (1.f / 2048.f) + EPS);
;         if (lane == 0) { stats[2 * m] = mean; stats[2 * m + 1] = rstd; }
.LBB0_1089:
	s_waitcnt lgkmcnt(0)
	global_load_dwordx4 v[10:13], v[2:3], off
	global_load_dwordx4 v[14:17], v[2:3], off offset:1024
	global_load_dwordx4 v[18:21], v[2:3], off offset:2048
	global_load_dwordx4 v[22:25], v[2:3], off offset:3072
	s_waitcnt vmcnt(3)
	v_lshlrev_b32_e32 v26, 16, v10
	v_and_b32_e32 v27, 0xffff0000, v10
	v_add_f32_e32 v10, 0, v26
	v_lshlrev_b32_e32 v28, 16, v11
	v_add_f32_e32 v10, v10, v27
	v_and_b32_e32 v11, 0xffff0000, v11
	v_add_f32_e32 v10, v10, v28
	v_lshlrev_b32_e32 v29, 16, v12
	v_add_f32_e32 v10, v10, v11
	v_and_b32_e32 v12, 0xffff0000, v12
	v_add_f32_e32 v10, v10, v29
	v_lshlrev_b32_e32 v30, 16, v13
	v_add_f32_e32 v10, v10, v12
	v_and_b32_e32 v13, 0xffff0000, v13
	v_add_f32_e32 v10, v10, v30
	s_waitcnt vmcnt(2)
	v_lshlrev_b32_e32 v31, 16, v14
	v_add_f32_e32 v10, v10, v13
	v_and_b32_e32 v14, 0xffff0000, v14
	v_add_f32_e32 v10, v10, v31
	v_lshlrev_b32_e32 v32, 16, v15
	v_add_f32_e32 v10, v10, v14
	v_and_b32_e32 v15, 0xffff0000, v15
	v_add_f32_e32 v10, v10, v32
	v_lshlrev_b32_e32 v33, 16, v16
	v_add_f32_e32 v10, v10, v15
	v_and_b32_e32 v16, 0xffff0000, v16
	v_add_f32_e32 v10, v10, v33
	v_lshlrev_b32_e32 v34, 16, v17
	v_add_f32_e32 v10, v10, v16
	v_and_b32_e32 v17, 0xffff0000, v17
	v_add_f32_e32 v10, v10, v34
	s_waitcnt vmcnt(1)
	v_lshlrev_b32_e32 v35, 16, v18
	v_add_f32_e32 v10, v10, v17
	v_and_b32_e32 v18, 0xffff0000, v18
	v_add_f32_e32 v10, v10, v35
	v_lshlrev_b32_e32 v36, 16, v19
	v_add_f32_e32 v10, v10, v18
	v_and_b32_e32 v19, 0xffff0000, v19
	v_add_f32_e32 v10, v10, v36
	v_lshlrev_b32_e32 v37, 16, v20
	v_add_f32_e32 v10, v10, v19
	v_and_b32_e32 v20, 0xffff0000, v20
	v_add_f32_e32 v10, v10, v37
	v_lshlrev_b32_e32 v38, 16, v21
	v_add_f32_e32 v10, v10, v20
	v_and_b32_e32 v21, 0xffff0000, v21
	v_add_f32_e32 v10, v10, v38
	s_waitcnt vmcnt(0)
	v_lshlrev_b32_e32 v39, 16, v22
	v_add_f32_e32 v10, v10, v21
	v_and_b32_e32 v22, 0xffff0000, v22
	v_add_f32_e32 v10, v10, v39
	v_lshlrev_b32_e32 v40, 16, v23
	v_add_f32_e32 v10, v10, v22
	v_and_b32_e32 v23, 0xffff0000, v23
	v_add_f32_e32 v10, v10, v40
	v_lshlrev_b32_e32 v41, 16, v24
	v_add_f32_e32 v10, v10, v23
	v_and_b32_e32 v24, 0xffff0000, v24
	v_add_f32_e32 v10, v10, v41
	v_lshlrev_b32_e32 v42, 16, v25
	v_add_f32_e32 v10, v10, v24
	v_and_b32_e32 v25, 0xffff0000, v25
	v_add_f32_e32 v10, v10, v42
	v_add_f32_e32 v10, v10, v25
	s_waitcnt lgkmcnt(0)
	s_nop 1
	v_add_f32_dpp v10, v10, v10 quad_perm:[1,0,3,2] row_mask:0xf bank_mask:0xf
	s_waitcnt lgkmcnt(0)
	s_nop 1
	v_add_f32_dpp v10, v10, v10 quad_perm:[2,3,0,1] row_mask:0xf bank_mask:0xf
	s_waitcnt lgkmcnt(0)
	s_nop 1
	v_add_f32_dpp v10, v10, v10 row_half_mirror row_mask:0xf bank_mask:0xf
	s_waitcnt lgkmcnt(0)
	s_nop 1
	v_add_f32_dpp v10, v10, v10 row_mirror row_mask:0xf bank_mask:0xf
	ds_bpermute_b32 v43, v8, v10
	s_waitcnt lgkmcnt(0)
	v_add_f32_e32 v10, v10, v43
	ds_bpermute_b32 v43, v9, v10
	s_waitcnt lgkmcnt(0)
	v_add_f32_e32 v10, v10, v43
	v_fmac_f32_e32 v27, 0xba000000, v10
	v_fmac_f32_e32 v26, 0xba000000, v10
	v_mul_f32_e32 v27, v27, v27
	v_fmac_f32_e32 v28, 0xba000000, v10
	v_fmac_f32_e32 v27, v26, v26
	v_fmac_f32_e32 v11, 0xba000000, v10
	v_fmac_f32_e32 v27, v28, v28
	v_fmac_f32_e32 v29, 0xba000000, v10
	v_fmac_f32_e32 v27, v11, v11
	v_fmac_f32_e32 v12, 0xba000000, v10
	v_fmac_f32_e32 v27, v29, v29
	v_fmac_f32_e32 v30, 0xba000000, v10
	v_fmac_f32_e32 v27, v12, v12
	v_fmac_f32_e32 v13, 0xba000000, v10
	v_fmac_f32_e32 v27, v30, v30
	v_fmac_f32_e32 v31, 0xba000000, v10
	v_fmac_f32_e32 v27, v13, v13
	v_fmac_f32_e32 v14, 0xba000000, v10
	v_fmac_f32_e32 v27, v31, v31
	v_fmac_f32_e32 v32, 0xba000000, v10
	v_fmac_f32_e32 v27, v14, v14
	v_fmac_f32_e32 v15, 0xba000000, v10
	v_fmac_f32_e32 v27, v32, v32
	v_fmac_f32_e32 v33, 0xba000000, v10
	v_fmac_f32_e32 v27, v15, v15
	v_fmac_f32_e32 v16, 0xba000000, v10
	v_fmac_f32_e32 v27, v33, v33
	v_fmac_f32_e32 v34, 0xba000000, v10
	v_fmac_f32_e32 v27, v16, v16
	v_fmac_f32_e32 v17, 0xba000000, v10
	v_fmac_f32_e32 v27, v34, v34
	v_fmac_f32_e32 v35, 0xba000000, v10
	v_fmac_f32_e32 v27, v17, v17
	v_fmac_f32_e32 v18, 0xba000000, v10
	v_fmac_f32_e32 v27, v35, v35
	v_fmac_f32_e32 v36, 0xba000000, v10
	v_fmac_f32_e32 v27, v18, v18
	v_fmac_f32_e32 v19, 0xba000000, v10
	v_fmac_f32_e32 v27, v36, v36
	v_fmac_f32_e32 v37, 0xba000000, v10
	v_fmac_f32_e32 v27, v19, v19
	v_fmac_f32_e32 v20, 0xba000000, v10
	v_fmac_f32_e32 v27, v37, v37
	v_fmac_f32_e32 v38, 0xba000000, v10
	v_fmac_f32_e32 v27, v20, v20
	v_fmac_f32_e32 v21, 0xba000000, v10
	v_fmac_f32_e32 v27, v38, v38
	v_fmac_f32_e32 v39, 0xba000000, v10
	v_fmac_f32_e32 v27, v21, v21
	v_fmac_f32_e32 v22, 0xba000000, v10
	v_fmac_f32_e32 v27, v39, v39
	v_fmac_f32_e32 v40, 0xba000000, v10
	v_fmac_f32_e32 v27, v22, v22
	v_fmac_f32_e32 v23, 0xba000000, v10
	v_fmac_f32_e32 v27, v40, v40
	v_fmac_f32_e32 v41, 0xba000000, v10
	v_fmac_f32_e32 v27, v23, v23
	v_fmac_f32_e32 v24, 0xba000000, v10
	v_fmac_f32_e32 v27, v41, v41
	v_fmac_f32_e32 v42, 0xba000000, v10
	v_fmac_f32_e32 v27, v24, v24
	v_fmac_f32_e32 v27, v42, v42
	v_fmac_f32_e32 v25, 0xba000000, v10
	v_fmac_f32_e32 v27, v25, v25
	s_waitcnt lgkmcnt(0)
	s_nop 1
	v_add_f32_dpp v11, v27, v27 quad_perm:[1,0,3,2] row_mask:0xf bank_mask:0xf
	s_waitcnt lgkmcnt(0)
	s_nop 1
	v_add_f32_dpp v11, v11, v11 quad_perm:[2,3,0,1] row_mask:0xf bank_mask:0xf
	s_waitcnt lgkmcnt(0)
	s_nop 1
	v_add_f32_dpp v11, v11, v11 row_half_mirror row_mask:0xf bank_mask:0xf
	s_waitcnt lgkmcnt(0)
	s_nop 1
	v_add_f32_dpp v11, v11, v11 row_mirror row_mask:0xf bank_mask:0xf
	ds_bpermute_b32 v12, v8, v11
	s_waitcnt lgkmcnt(0)
	v_add_f32_e32 v11, v11, v12
	ds_bpermute_b32 v12, v9, v11
	s_and_saveexec_b64 s[14:15], vcc
	s_cbranch_execz .LBB0_1088
	s_waitcnt lgkmcnt(0)
	v_add_f32_e32 v11, v11, v12
	v_fmamk_f32 v11, v11, 0x3a000000, v0
	v_mul_f32_e32 v12, 0x4b800000, v11
	v_cmp_gt_f32_e64 s[8:9], s5, v11
	s_ashr_i32 s11, s10, 31
	s_lshl_b64 s[20:21], s[10:11], 2
	v_cndmask_b32_e64 v11, v11, v12, s[8:9]
	v_rsq_f32_e32 v11, v11
	s_add_u32 s20, s16, s20
	v_mul_f32_e32 v10, 0x3a000000, v10
	s_addc_u32 s21, s17, s21
	v_mul_f32_e32 v12, 0x45800000, v11
	v_cndmask_b32_e64 v11, v11, v12, s[8:9]
	global_store_dwordx2 v1, v[10:11], s[20:21]
	s_branch .LBB0_1088

; #define LAS __attribute__((address_space(3)))
; DI unsigned pk2(float lo, float hi) { return pg8::cvt_pk_bf16(lo, hi); }
; DI float bflo(unsigned w) { return __uint_as_float(w << 16); }
; DI float bfhi(unsigned w) { return __uint_as_float(w & 0xffff0000u); }
; DI void sg_mix(const P& p, const bf16_t* Z, const float* stats, bf16_t* Y, LAS unsigned char* L) {
;     ...
;         u32x4 vq[8];
;         { const bf16_t* zp = Z + (base + (tid >> 5)) * 4096 + 2048 + g * 256 + (tid & 31) * 8;
; #pragma unroll
;           for (int j = 0; j < 8; ++j) vq[j] = *(const u32x4*)(zp + (size_t)(16 * j) * 4096); }
;         f32x4 wv[8], st0[8], st1[8];
; #pragma unroll
;         for (int j = 0; j < 8; ++j) { const int idx = tid + 512 * j, t = idx >> 5, s4 = (idx & 31) * 4;
;             wv[j] = *(const f32x4*)(p.sg_w_pos + ((size_t)g * 128 + t) * 128 + s4);
;             st0[j] = *(const f32x4*)(stats + 2 * (base + s4)); st1[j] = *(const f32x4*)(stats + 2 * (base + s4) + 4); }
;         __syncthreads();
; #pragma unroll
;         for (int j = 0; j < 8; ++j) { const int idx = tid + 512 * j, t = idx >> 5, s4 = (idx & 31) * 4;
;             const float w0 = s4 <= t ? wv[j].x : 0.f, w1 = s4 + 1 <= t ? wv[j].y : 0.f, w2 = s4 + 2 <= t ? wv[j].z : 0.f, w3 = s4 + 3 <= t ? wv[j].w : 0.f;
;             u32x2 o; o.x = pk2(w0 * st0[j].y, w1 * st0[j].w); o.y = pk2(w2 * st1[j].y, w3 * st1[j].w);
;             *(LAS u32x2*)(Wp + t * 272 + s4 * 2) = o;
;             float a = bflo(o.x) * st0[j].x + bfhi(o.x) * st0[j].z + bflo(o.y) * st1[j].x + bfhi(o.y) * st1[j].z;
;             float bsum = (w0 + w1) + (w2 + w3);
; #pragma unroll
;             for (int o2 = 1; o2 < 32; o2 <<= 1) { a += __shfl_xor(a, o2); bsum += __shfl_xor(bsum, o2); }
;             if ((lane & 31) == 0) { At[t] = a; Bt[t] = bsum; } }
.LBB0_1146:
	s_ashr_i32 s76, s80, 3
	s_ashr_i32 s77, s76, 31
	s_lshl_b64 s[76:77], s[76:77], 7
	v_lshl_add_u64 v[0:1], s[76:77], 0, v[74:75]
	s_and_b32 s81, s80, 7
	v_lshlrev_b64 v[0:1], 13, v[0:1]
	v_lshl_add_u64 v[0:1], s[92:93], 0, v[0:1]
	s_lshl_b32 s4, s81, 9
	v_lshl_add_u64 v[0:1], v[0:1], 0, s[4:5]
	v_lshl_add_u64 v[12:13], v[0:1], 0, v[76:77]
	v_add_co_u32_e32 v0, vcc, 0x1000, v12
	s_lshl_b32 s4, s81, 7
	s_nop 0
	v_addc_co_u32_e32 v1, vcc, 0, v13, vcc
	global_load_dwordx4 v[16:19], v[0:1], off
	v_add_co_u32_e32 v0, vcc, 0x21000, v12
	v_lshl_add_u64 v[40:41], s[4:5], 0, v[74:75]
	s_nop 0
	v_addc_co_u32_e32 v1, vcc, 0, v13, vcc
	global_load_dwordx4 v[20:23], v[0:1], off
	v_add_co_u32_e32 v0, vcc, 0x41000, v12
	v_mov_b32_e32 v33, s77
	s_nop 0
	v_addc_co_u32_e32 v1, vcc, 0, v13, vcc
	global_load_dwordx4 v[24:27], v[0:1], off
	v_add_co_u32_e32 v0, vcc, 0x61000, v12
	v_or_b32_e32 v32, s76, v78
	s_nop 0
	v_addc_co_u32_e32 v1, vcc, 0, v13, vcc
	global_load_dwordx4 v[28:31], v[0:1], off
	v_add_co_u32_e32 v0, vcc, 0x81000, v12
	v_lshlrev_b64 v[40:41], 9, v[40:41]
	s_nop 0
	v_addc_co_u32_e32 v1, vcc, 0, v13, vcc
	v_add_co_u32_e32 v4, vcc, 0xa1000, v12
	v_lshl_add_u64 v[36:37], v[32:33], 3, s[88:89]
	s_nop 0
	v_addc_co_u32_e32 v5, vcc, 0, v13, vcc
	v_add_co_u32_e32 v8, vcc, 0xc1000, v12
	v_lshl_add_u64 v[40:41], v[104:105], 0, v[40:41]
	s_nop 0
	v_addc_co_u32_e32 v9, vcc, 0, v13, vcc
	v_add_co_u32_e32 v12, vcc, 0xe1000, v12
	global_load_dwordx4 v[0:3], v[0:1], off
	s_nop 0
	v_addc_co_u32_e32 v13, vcc, 0, v13, vcc
	global_load_dwordx4 v[4:7], v[4:5], off
	s_nop 0
	global_load_dwordx4 v[8:11], v[8:9], off
	s_nop 0
	global_load_dwordx4 v[12:15], v[12:13], off
	s_nop 0
	global_load_dwordx4 v[32:35], v[36:37], off offset:16
	s_nop 0
	global_load_dwordx4 v[36:39], v[36:37], off
	s_nop 0
	global_load_dwordx4 v[68:71], v[40:41], off
	v_lshl_add_u64 v[40:41], s[4:5], 0, v[84:85]
	v_lshlrev_b64 v[40:41], 9, v[40:41]
	v_lshl_add_u64 v[40:41], v[104:105], 0, v[40:41]
	global_load_dwordx4 v[64:67], v[40:41], off
	v_lshl_add_u64 v[40:41], s[4:5], 0, v[86:87]
	v_lshlrev_b64 v[40:41], 9, v[40:41]
	v_lshl_add_u64 v[40:41], v[104:105], 0, v[40:41]
	global_load_dwordx4 v[60:63], v[40:41], off
	v_lshl_add_u64 v[40:41], s[4:5], 0, v[88:89]
	v_lshlrev_b64 v[40:41], 9, v[40:41]
	v_lshl_add_u64 v[40:41], v[104:105], 0, v[40:41]
	global_load_dwordx4 v[56:59], v[40:41], off
	v_lshl_add_u64 v[40:41], s[4:5], 0, v[90:91]
	v_lshlrev_b64 v[40:41], 9, v[40:41]
	v_lshl_add_u64 v[40:41], v[104:105], 0, v[40:41]
	global_load_dwordx4 v[52:55], v[40:41], off
	v_lshl_add_u64 v[40:41], s[4:5], 0, v[92:93]
	v_lshlrev_b64 v[40:41], 9, v[40:41]
	v_lshl_add_u64 v[40:41], v[104:105], 0, v[40:41]
	global_load_dwordx4 v[48:51], v[40:41], off
	v_lshl_add_u64 v[40:41], s[4:5], 0, v[94:95]
	v_lshlrev_b64 v[40:41], 9, v[40:41]
	v_lshl_add_u64 v[40:41], v[104:105], 0, v[40:41]
	global_load_dwordx4 v[44:47], v[40:41], off
	v_lshl_add_u64 v[40:41], s[4:5], 0, v[96:97]
	v_lshlrev_b64 v[40:41], 9, v[40:41]
	v_lshl_add_u64 v[40:41], v[104:105], 0, v[40:41]
	global_load_dwordx4 v[40:43], v[40:41], off
	s_barrier
	s_waitcnt vmcnt(7)
	v_cndmask_b32_e64 v111, 0, v69, s[8:9]
	v_cndmask_b32_e64 v110, v68, 0, s[10:11]
	v_mov_b32_e32 v68, v37
	v_mov_b32_e32 v69, v39
	v_pk_mul_f32 v[68:69], v[68:69], v[110:111]
	v_cndmask_b32_e64 v71, v71, 0, s[12:13]
	v_cvt_pk_bf16_f32 v112, v68, v69
	v_cndmask_b32_e64 v70, v70, 0, s[14:15]
	v_mov_b32_e32 v68, v33
	v_mov_b32_e32 v69, v35
	v_pk_mul_f32 v[114:115], v[68:69], v[70:71]
	v_and_b32_e32 v35, 0xffff0000, v112
	v_cvt_pk_bf16_f32 v113, v114, v115
	v_lshlrev_b32_e32 v33, 16, v112
	v_mul_f32_e32 v35, v38, v35
	v_fmac_f32_e32 v35, v36, v33
	v_lshlrev_b32_e32 v33, 16, v113
	v_fmac_f32_e32 v35, v32, v33
	v_and_b32_e32 v33, 0xffff0000, v113
	v_fmac_f32_e32 v35, v34, v33
	v_add_f32_e32 v33, v70, v71
	v_add_f32_e32 v70, v110, v111
	v_add_f32_e32 v33, v70, v33
	ds_write_b64 v150, v[112:113]
	s_waitcnt lgkmcnt(1)
	s_nop 1
	v_add_f32_dpp v35, v35, v35 quad_perm:[1,0,3,2] row_mask:0xf bank_mask:0xf
	s_waitcnt lgkmcnt(0)
	s_nop 1
	v_add_f32_dpp v33, v33, v33 quad_perm:[1,0,3,2] row_mask:0xf bank_mask:0xf
	s_waitcnt lgkmcnt(0)
	s_nop 1
	v_add_f32_dpp v35, v35, v35 quad_perm:[2,3,0,1] row_mask:0xf bank_mask:0xf
	s_waitcnt lgkmcnt(0)
	s_nop 1
	v_add_f32_dpp v33, v33, v33 quad_perm:[2,3,0,1] row_mask:0xf bank_mask:0xf
	s_waitcnt lgkmcnt(0)
	s_nop 1
	v_add_f32_dpp v35, v35, v35 row_half_mirror row_mask:0xf bank_mask:0xf
	s_waitcnt lgkmcnt(0)
	s_nop 1
	v_add_f32_dpp v70, v33, v33 row_half_mirror row_mask:0xf bank_mask:0xf
	s_waitcnt lgkmcnt(0)
	s_nop 1
	v_add_f32_dpp v33, v35, v35 row_mirror row_mask:0xf bank_mask:0xf
	s_waitcnt lgkmcnt(0)
	s_nop 1
	v_add_f32_dpp v35, v70, v70 row_mirror row_mask:0xf bank_mask:0xf
	ds_bpermute_b32 v70, v103, v33
	ds_bpermute_b32 v71, v103, v35
	s_and_saveexec_b64 s[78:79], s[6:7]
	s_cbranch_execz .LBB0_1148
	s_waitcnt lgkmcnt(1)
	v_add_f32_e32 v33, v33, v70
	s_waitcnt lgkmcnt(0)
	v_add_f32_e32 v35, v35, v71
	ds_write_b32 v127, v33
	ds_write_b32 v126, v35
; #define LAS __attribute__((address_space(3)))
; DI unsigned pk2(float lo, float hi) { return pg8::cvt_pk_bf16(lo, hi); }
; DI float bflo(unsigned w) { return __uint_as_float(w << 16); }
; DI float bfhi(unsigned w) { return __uint_as_float(w & 0xffff0000u); }
; DI void sg_mix(const P& p, const bf16_t* Z, const float* stats, bf16_t* Y, LAS unsigned char* L) {
;     ...
;         for (int j = 0; j < 8; ++j) { const int idx = tid + 512 * j, t = idx >> 5, s4 = (idx & 31) * 4;
;             const float w0 = s4 <= t ? wv[j].x : 0.f, w1 = s4 + 1 <= t ? wv[j].y : 0.f, w2 = s4 + 2 <= t ? wv[j].z : 0.f, w3 = s4 + 3 <= t ? wv[j].w : 0.f;
;             u32x2 o; o.x = pk2(w0 * st0[j].y, w1 * st0[j].w); o.y = pk2(w2 * st1[j].y, w3 * st1[j].w);
;             *(LAS u32x2*)(Wp + t * 272 + s4 * 2) = o;
;             float a = bflo(o.x) * st0[j].x + bfhi(o.x) * st0[j].z + bflo(o.y) * st1[j].x + bfhi(o.y) * st1[j].z;
;             float bsum = (w0 + w1) + (w2 + w3);
; #pragma unroll
;             for (int o2 = 1; o2 < 32; o2 <<= 1) { a += __shfl_xor(a, o2); bsum += __shfl_xor(bsum, o2); }
;             if ((lane & 31) == 0) { At[t] = a; Bt[t] = bsum; } }
.LBB0_1148:
	s_or_b64 exec, exec, s[78:79]
	s_waitcnt vmcnt(6)
	v_cndmask_b32_e64 v33, v64, 0, s[16:17]
	v_cndmask_b32_e64 v35, 0, v65, s[18:19]
	v_cndmask_b32_e64 v67, v67, 0, s[20:21]
	v_cndmask_b32_e64 v66, v66, 0, s[22:23]
	v_mul_f32_e32 v64, v37, v33
	v_mul_f32_e32 v65, v39, v35
	s_waitcnt lgkmcnt(0)
	v_pk_mul_f32 v[70:71], v[68:69], v[66:67]
	v_cvt_pk_bf16_f32 v64, v64, v65
	v_cvt_pk_bf16_f32 v65, v70, v71
	ds_write_b64 v151, v[64:65]
	v_lshlrev_b32_e32 v70, 16, v64
	v_and_b32_e32 v64, 0xffff0000, v64
	v_mul_f32_e32 v64, v38, v64
	v_fmac_f32_e32 v64, v36, v70
	v_lshlrev_b32_e32 v70, 16, v65
	v_fmac_f32_e32 v64, v32, v70
	v_and_b32_e32 v65, 0xffff0000, v65
	v_fmac_f32_e32 v64, v34, v65
	v_add_f32_e32 v33, v33, v35
	v_add_f32_e32 v35, v66, v67
	v_add_f32_e32 v33, v33, v35
	s_waitcnt lgkmcnt(0)
	s_nop 1
	v_add_f32_dpp v35, v64, v64 quad_perm:[1,0,3,2] row_mask:0xf bank_mask:0xf
	s_waitcnt lgkmcnt(0)
	s_nop 1
	v_add_f32_dpp v33, v33, v33 quad_perm:[1,0,3,2] row_mask:0xf bank_mask:0xf
	s_waitcnt lgkmcnt(0)
	s_nop 1
	v_add_f32_dpp v35, v35, v35 quad_perm:[2,3,0,1] row_mask:0xf bank_mask:0xf
	s_waitcnt lgkmcnt(0)
	s_nop 1
	v_add_f32_dpp v33, v33, v33 quad_perm:[2,3,0,1] row_mask:0xf bank_mask:0xf
	s_waitcnt lgkmcnt(0)
	s_nop 1
	v_add_f32_dpp v35, v35, v35 row_half_mirror row_mask:0xf bank_mask:0xf
	s_waitcnt lgkmcnt(0)
	s_nop 1
	v_add_f32_dpp v64, v33, v33 row_half_mirror row_mask:0xf bank_mask:0xf
	s_waitcnt lgkmcnt(0)
	s_nop 1
	v_add_f32_dpp v33, v35, v35 row_mirror row_mask:0xf bank_mask:0xf
	s_waitcnt lgkmcnt(0)
	s_nop 1
	v_add_f32_dpp v35, v64, v64 row_mirror row_mask:0xf bank_mask:0xf
	ds_bpermute_b32 v64, v103, v33
	ds_bpermute_b32 v65, v103, v35
	s_and_saveexec_b64 s[78:79], s[6:7]
	s_cbranch_execz .LBB0_1150
	s_waitcnt lgkmcnt(1)
	v_add_f32_e32 v33, v33, v64
	s_waitcnt lgkmcnt(0)
	v_add_f32_e32 v35, v35, v65
	ds_write_b32 v129, v33
	ds_write_b32 v128, v35
.LBB0_1150:
	s_or_b64 exec, exec, s[78:79]
	s_waitcnt vmcnt(5)
	v_cndmask_b32_e64 v33, v60, 0, s[24:25]
	v_cndmask_b32_e64 v35, 0, v61, s[26:27]
	v_cndmask_b32_e64 v63, v63, 0, s[28:29]
	v_cndmask_b32_e64 v62, v62, 0, s[30:31]
	v_mul_f32_e32 v60, v37, v33
	v_mul_f32_e32 v61, v39, v35
	s_waitcnt lgkmcnt(0)
	v_pk_mul_f32 v[64:65], v[68:69], v[62:63]
	v_cvt_pk_bf16_f32 v60, v60, v61
	v_cvt_pk_bf16_f32 v61, v64, v65
	ds_write_b64 v152, v[60:61]
	v_lshlrev_b32_e32 v64, 16, v60
	v_and_b32_e32 v60, 0xffff0000, v60
	v_mul_f32_e32 v60, v38, v60
	v_fmac_f32_e32 v60, v36, v64
	v_lshlrev_b32_e32 v64, 16, v61
	v_fmac_f32_e32 v60, v32, v64
	v_and_b32_e32 v61, 0xffff0000, v61
	v_fmac_f32_e32 v60, v34, v61
	v_add_f32_e32 v33, v33, v35
	v_add_f32_e32 v35, v62, v63
	v_add_f32_e32 v33, v33, v35
	s_waitcnt lgkmcnt(0)
	s_nop 1
	v_add_f32_dpp v35, v60, v60 quad_perm:[1,0,3,2] row_mask:0xf bank_mask:0xf
	s_waitcnt lgkmcnt(0)
	s_nop 1
	v_add_f32_dpp v33, v33, v33 quad_perm:[1,0,3,2] row_mask:0xf bank_mask:0xf
	s_waitcnt lgkmcnt(0)
	s_nop 1
	v_add_f32_dpp v35, v35, v35 quad_perm:[2,3,0,1] row_mask:0xf bank_mask:0xf
	s_waitcnt lgkmcnt(0)
	s_nop 1
	v_add_f32_dpp v33, v33, v33 quad_perm:[2,3,0,1] row_mask:0xf bank_mask:0xf
	s_waitcnt lgkmcnt(0)
	s_nop 1
	v_add_f32_dpp v35, v35, v35 row_half_mirror row_mask:0xf bank_mask:0xf
	s_waitcnt lgkmcnt(0)
	s_nop 1
	v_add_f32_dpp v60, v33, v33 row_half_mirror row_mask:0xf bank_mask:0xf
	s_waitcnt lgkmcnt(0)
	s_nop 1
	v_add_f32_dpp v33, v35, v35 row_mirror row_mask:0xf bank_mask:0xf
	s_waitcnt lgkmcnt(0)
	s_nop 1
	v_add_f32_dpp v35, v60, v60 row_mirror row_mask:0xf bank_mask:0xf
	ds_bpermute_b32 v60, v103, v33
	ds_bpermute_b32 v61, v103, v35
	s_and_saveexec_b64 s[78:79], s[6:7]
	s_cbranch_execz .LBB0_1152
	s_waitcnt lgkmcnt(1)
	v_add_f32_e32 v33, v33, v60
	s_waitcnt lgkmcnt(0)
	v_add_f32_e32 v35, v35, v61
	ds_write_b32 v131, v33
	ds_write_b32 v130, v35
.LBB0_1152:
	s_or_b64 exec, exec, s[78:79]
	s_waitcnt vmcnt(4)
	v_cndmask_b32_e64 v33, v56, 0, s[34:35]
	v_cndmask_b32_e64 v35, 0, v57, s[36:37]
	v_cndmask_b32_e64 v59, v59, 0, s[38:39]
	v_cndmask_b32_e64 v58, v58, 0, s[40:41]
	v_mul_f32_e32 v56, v37, v33
	v_mul_f32_e32 v57, v39, v35
	s_waitcnt lgkmcnt(0)
	v_pk_mul_f32 v[60:61], v[68:69], v[58:59]
	v_cvt_pk_bf16_f32 v56, v56, v57
	v_cvt_pk_bf16_f32 v57, v60, v61
	ds_write_b64 v153, v[56:57]
	v_lshlrev_b32_e32 v60, 16, v56
	v_and_b32_e32 v56, 0xffff0000, v56
	v_mul_f32_e32 v56, v38, v56
	v_fmac_f32_e32 v56, v36, v60
	v_lshlrev_b32_e32 v60, 16, v57
	v_fmac_f32_e32 v56, v32, v60
	v_and_b32_e32 v57, 0xffff0000, v57
	v_fmac_f32_e32 v56, v34, v57
	v_add_f32_e32 v33, v33, v35
	v_add_f32_e32 v35, v58, v59
	v_add_f32_e32 v33, v33, v35
	s_waitcnt lgkmcnt(0)
	s_nop 1
	v_add_f32_dpp v35, v56, v56 quad_perm:[1,0,3,2] row_mask:0xf bank_mask:0xf
	s_waitcnt lgkmcnt(0)
	s_nop 1
	v_add_f32_dpp v33, v33, v33 quad_perm:[1,0,3,2] row_mask:0xf bank_mask:0xf
	s_waitcnt lgkmcnt(0)
	s_nop 1
	v_add_f32_dpp v35, v35, v35 quad_perm:[2,3,0,1] row_mask:0xf bank_mask:0xf
	s_waitcnt lgkmcnt(0)
	s_nop 1
	v_add_f32_dpp v33, v33, v33 quad_perm:[2,3,0,1] row_mask:0xf bank_mask:0xf
	s_waitcnt lgkmcnt(0)
	s_nop 1
	v_add_f32_dpp v35, v35, v35 row_half_mirror row_mask:0xf bank_mask:0xf
	s_waitcnt lgkmcnt(0)
	s_nop 1
	v_add_f32_dpp v56, v33, v33 row_half_mirror row_mask:0xf bank_mask:0xf
	s_waitcnt lgkmcnt(0)
	s_nop 1
	v_add_f32_dpp v33, v35, v35 row_mirror row_mask:0xf bank_mask:0xf
	s_waitcnt lgkmcnt(0)
	s_nop 1
	v_add_f32_dpp v35, v56, v56 row_mirror row_mask:0xf bank_mask:0xf
	ds_bpermute_b32 v56, v103, v33
	ds_bpermute_b32 v57, v103, v35
	s_and_saveexec_b64 s[78:79], s[6:7]
	s_cbranch_execz .LBB0_1154
	s_waitcnt lgkmcnt(1)
	v_add_f32_e32 v33, v33, v56
	s_waitcnt lgkmcnt(0)
	v_add_f32_e32 v35, v35, v57
	ds_write_b32 v133, v33
	ds_write_b32 v132, v35
; #define LAS __attribute__((address_space(3)))
; DI unsigned pk2(float lo, float hi) { return pg8::cvt_pk_bf16(lo, hi); }
; DI float bflo(unsigned w) { return __uint_as_float(w << 16); }
; DI float bfhi(unsigned w) { return __uint_as_float(w & 0xffff0000u); }
; DI void sg_mix(const P& p, const bf16_t* Z, const float* stats, bf16_t* Y, LAS unsigned char* L) {
;     ...
;         for (int j = 0; j < 8; ++j) { const int idx = tid + 512 * j, t = idx >> 5, s4 = (idx & 31) * 4;
;             const float w0 = s4 <= t ? wv[j].x : 0.f, w1 = s4 + 1 <= t ? wv[j].y : 0.f, w2 = s4 + 2 <= t ? wv[j].z : 0.f, w3 = s4 + 3 <= t ? wv[j].w : 0.f;
;             u32x2 o; o.x = pk2(w0 * st0[j].y, w1 * st0[j].w); o.y = pk2(w2 * st1[j].y, w3 * st1[j].w);
;             *(LAS u32x2*)(Wp + t * 272 + s4 * 2) = o;
;             float a = bflo(o.x) * st0[j].x + bfhi(o.x) * st0[j].z + bflo(o.y) * st1[j].x + bfhi(o.y) * st1[j].z;
;             float bsum = (w0 + w1) + (w2 + w3);
; #pragma unroll
;             for (int o2 = 1; o2 < 32; o2 <<= 1) { a += __shfl_xor(a, o2); bsum += __shfl_xor(bsum, o2); }
;             if ((lane & 31) == 0) { At[t] = a; Bt[t] = bsum; } }
.LBB0_1154:
	s_or_b64 exec, exec, s[78:79]
	s_waitcnt vmcnt(3)
	v_cndmask_b32_e64 v33, v52, 0, s[42:43]
	v_cndmask_b32_e64 v35, 0, v53, s[44:45]
	v_cndmask_b32_e64 v55, v55, 0, s[46:47]
	v_cndmask_b32_e64 v54, v54, 0, s[48:49]
	v_mul_f32_e32 v52, v37, v33
	v_mul_f32_e32 v53, v39, v35
	s_waitcnt lgkmcnt(0)
	v_pk_mul_f32 v[56:57], v[68:69], v[54:55]
	v_cvt_pk_bf16_f32 v52, v52, v53
	v_cvt_pk_bf16_f32 v53, v56, v57
	ds_write_b64 v154, v[52:53]
	v_lshlrev_b32_e32 v56, 16, v52
	v_and_b32_e32 v52, 0xffff0000, v52
	v_mul_f32_e32 v52, v38, v52
	v_fmac_f32_e32 v52, v36, v56
	v_lshlrev_b32_e32 v56, 16, v53
	v_fmac_f32_e32 v52, v32, v56
	v_and_b32_e32 v53, 0xffff0000, v53
	v_fmac_f32_e32 v52, v34, v53
	v_add_f32_e32 v33, v33, v35
	v_add_f32_e32 v35, v54, v55
	v_add_f32_e32 v33, v33, v35
	s_waitcnt lgkmcnt(0)
	s_nop 1
	v_add_f32_dpp v35, v52, v52 quad_perm:[1,0,3,2] row_mask:0xf bank_mask:0xf
	s_waitcnt lgkmcnt(0)
	s_nop 1
	v_add_f32_dpp v33, v33, v33 quad_perm:[1,0,3,2] row_mask:0xf bank_mask:0xf
	s_waitcnt lgkmcnt(0)
	s_nop 1
	v_add_f32_dpp v35, v35, v35 quad_perm:[2,3,0,1] row_mask:0xf bank_mask:0xf
	s_waitcnt lgkmcnt(0)
	s_nop 1
	v_add_f32_dpp v33, v33, v33 quad_perm:[2,3,0,1] row_mask:0xf bank_mask:0xf
	s_waitcnt lgkmcnt(0)
	s_nop 1
	v_add_f32_dpp v35, v35, v35 row_half_mirror row_mask:0xf bank_mask:0xf
	s_waitcnt lgkmcnt(0)
	s_nop 1
	v_add_f32_dpp v52, v33, v33 row_half_mirror row_mask:0xf bank_mask:0xf
	s_waitcnt lgkmcnt(0)
	s_nop 1
	v_add_f32_dpp v33, v35, v35 row_mirror row_mask:0xf bank_mask:0xf
	s_waitcnt lgkmcnt(0)
	s_nop 1
	v_add_f32_dpp v35, v52, v52 row_mirror row_mask:0xf bank_mask:0xf
	ds_bpermute_b32 v52, v103, v33
	ds_bpermute_b32 v53, v103, v35
	s_and_saveexec_b64 s[78:79], s[6:7]
	s_cbranch_execz .LBB0_1156
	s_waitcnt lgkmcnt(1)
	v_add_f32_e32 v33, v33, v52
	s_waitcnt lgkmcnt(0)
	v_add_f32_e32 v35, v35, v53
	ds_write_b32 v135, v33
	ds_write_b32 v134, v35
.LBB0_1156:
	s_or_b64 exec, exec, s[78:79]
	s_waitcnt vmcnt(2)
	v_cndmask_b32_e64 v33, v48, 0, s[50:51]
	v_cndmask_b32_e64 v35, 0, v49, s[52:53]
	v_cndmask_b32_e64 v51, v51, 0, s[54:55]
	v_cndmask_b32_e64 v50, v50, 0, s[56:57]
	v_mul_f32_e32 v48, v37, v33
	v_mul_f32_e32 v49, v39, v35
	s_waitcnt lgkmcnt(0)
	v_pk_mul_f32 v[52:53], v[68:69], v[50:51]
	v_cvt_pk_bf16_f32 v48, v48, v49
	v_cvt_pk_bf16_f32 v49, v52, v53
	ds_write_b64 v155, v[48:49]
	v_lshlrev_b32_e32 v52, 16, v48
	v_and_b32_e32 v48, 0xffff0000, v48
	v_mul_f32_e32 v48, v38, v48
	v_fmac_f32_e32 v48, v36, v52
	v_lshlrev_b32_e32 v52, 16, v49
	v_fmac_f32_e32 v48, v32, v52
	v_and_b32_e32 v49, 0xffff0000, v49
	v_fmac_f32_e32 v48, v34, v49
	v_add_f32_e32 v33, v33, v35
	v_add_f32_e32 v35, v50, v51
	v_add_f32_e32 v33, v33, v35
	s_waitcnt lgkmcnt(0)
	s_nop 1
	v_add_f32_dpp v35, v48, v48 quad_perm:[1,0,3,2] row_mask:0xf bank_mask:0xf
	s_waitcnt lgkmcnt(0)
	s_nop 1
	v_add_f32_dpp v33, v33, v33 quad_perm:[1,0,3,2] row_mask:0xf bank_mask:0xf
	s_waitcnt lgkmcnt(0)
	s_nop 1
	v_add_f32_dpp v35, v35, v35 quad_perm:[2,3,0,1] row_mask:0xf bank_mask:0xf
	s_waitcnt lgkmcnt(0)
	s_nop 1
	v_add_f32_dpp v33, v33, v33 quad_perm:[2,3,0,1] row_mask:0xf bank_mask:0xf
	s_waitcnt lgkmcnt(0)
	s_nop 1
	v_add_f32_dpp v35, v35, v35 row_half_mirror row_mask:0xf bank_mask:0xf
	s_waitcnt lgkmcnt(0)
	s_nop 1
	v_add_f32_dpp v48, v33, v33 row_half_mirror row_mask:0xf bank_mask:0xf
	s_waitcnt lgkmcnt(0)
	s_nop 1
	v_add_f32_dpp v33, v35, v35 row_mirror row_mask:0xf bank_mask:0xf
	s_waitcnt lgkmcnt(0)
	s_nop 1
	v_add_f32_dpp v35, v48, v48 row_mirror row_mask:0xf bank_mask:0xf
	ds_bpermute_b32 v48, v103, v33
	ds_bpermute_b32 v49, v103, v35
	s_and_saveexec_b64 s[78:79], s[6:7]
	s_cbranch_execz .LBB0_1158
	s_waitcnt lgkmcnt(1)
	v_add_f32_e32 v33, v33, v48
	s_waitcnt lgkmcnt(0)
	v_add_f32_e32 v35, v35, v49
	ds_write_b32 v137, v33
	ds_write_b32 v136, v35
; #define LAS __attribute__((address_space(3)))
; DI unsigned pk2(float lo, float hi) { return pg8::cvt_pk_bf16(lo, hi); }
; DI float bflo(unsigned w) { return __uint_as_float(w << 16); }
; DI float bfhi(unsigned w) { return __uint_as_float(w & 0xffff0000u); }
; DI void sg_mix(const P& p, const bf16_t* Z, const float* stats, bf16_t* Y, LAS unsigned char* L) {
;     ...
;         for (int j = 0; j < 8; ++j) { const int idx = tid + 512 * j, t = idx >> 5, s4 = (idx & 31) * 4;
;             const float w0 = s4 <= t ? wv[j].x : 0.f, w1 = s4 + 1 <= t ? wv[j].y : 0.f, w2 = s4 + 2 <= t ? wv[j].z : 0.f, w3 = s4 + 3 <= t ? wv[j].w : 0.f;
;             u32x2 o; o.x = pk2(w0 * st0[j].y, w1 * st0[j].w); o.y = pk2(w2 * st1[j].y, w3 * st1[j].w);
;             *(LAS u32x2*)(Wp + t * 272 + s4 * 2) = o;
;             float a = bflo(o.x) * st0[j].x + bfhi(o.x) * st0[j].z + bflo(o.y) * st1[j].x + bfhi(o.y) * st1[j].z;
;             float bsum = (w0 + w1) + (w2 + w3);
; #pragma unroll
;             for (int o2 = 1; o2 < 32; o2 <<= 1) { a += __shfl_xor(a, o2); bsum += __shfl_xor(bsum, o2); }
;             if ((lane & 31) == 0) { At[t] = a; Bt[t] = bsum; } }
.LBB0_1158:
	s_or_b64 exec, exec, s[78:79]
	s_waitcnt vmcnt(1)
	v_cndmask_b32_e64 v33, v44, 0, s[58:59]
	v_cndmask_b32_e64 v35, 0, v45, s[60:61]
	v_cndmask_b32_e64 v47, v47, 0, s[62:63]
	v_cndmask_b32_e64 v46, v46, 0, s[64:65]
	v_mul_f32_e32 v44, v37, v33
	v_mul_f32_e32 v45, v39, v35
	s_waitcnt lgkmcnt(0)
	v_pk_mul_f32 v[48:49], v[68:69], v[46:47]
	v_cvt_pk_bf16_f32 v44, v44, v45
	v_cvt_pk_bf16_f32 v45, v48, v49
	ds_write_b64 v156, v[44:45]
	v_lshlrev_b32_e32 v48, 16, v44
	v_and_b32_e32 v44, 0xffff0000, v44
	v_mul_f32_e32 v44, v38, v44
	v_fmac_f32_e32 v44, v36, v48
	v_lshlrev_b32_e32 v48, 16, v45
	v_fmac_f32_e32 v44, v32, v48
	v_and_b32_e32 v45, 0xffff0000, v45
	v_fmac_f32_e32 v44, v34, v45
	v_add_f32_e32 v33, v33, v35
	v_add_f32_e32 v35, v46, v47
	v_add_f32_e32 v33, v33, v35
	s_waitcnt lgkmcnt(0)
	s_nop 1
	v_add_f32_dpp v35, v44, v44 quad_perm:[1,0,3,2] row_mask:0xf bank_mask:0xf
	s_waitcnt lgkmcnt(0)
	s_nop 1
	v_add_f32_dpp v33, v33, v33 quad_perm:[1,0,3,2] row_mask:0xf bank_mask:0xf
	s_waitcnt lgkmcnt(0)
	s_nop 1
	v_add_f32_dpp v35, v35, v35 quad_perm:[2,3,0,1] row_mask:0xf bank_mask:0xf
	s_waitcnt lgkmcnt(0)
	s_nop 1
	v_add_f32_dpp v33, v33, v33 quad_perm:[2,3,0,1] row_mask:0xf bank_mask:0xf
	s_waitcnt lgkmcnt(0)
	s_nop 1
	v_add_f32_dpp v35, v35, v35 row_half_mirror row_mask:0xf bank_mask:0xf
	s_waitcnt lgkmcnt(0)
	s_nop 1
	v_add_f32_dpp v44, v33, v33 row_half_mirror row_mask:0xf bank_mask:0xf
	s_waitcnt lgkmcnt(0)
	s_nop 1
	v_add_f32_dpp v33, v35, v35 row_mirror row_mask:0xf bank_mask:0xf
	s_waitcnt lgkmcnt(0)
	s_nop 1
	v_add_f32_dpp v35, v44, v44 row_mirror row_mask:0xf bank_mask:0xf
	ds_bpermute_b32 v44, v103, v33
	ds_bpermute_b32 v45, v103, v35
	s_and_saveexec_b64 s[78:79], s[6:7]
	s_cbranch_execz .LBB0_1160
	s_waitcnt lgkmcnt(1)
	v_add_f32_e32 v33, v33, v44
	s_waitcnt lgkmcnt(0)
	v_add_f32_e32 v35, v35, v45
	ds_write_b32 v139, v33
	ds_write_b32 v138, v35
.LBB0_1160:
	s_or_b64 exec, exec, s[78:79]
	s_waitcnt vmcnt(0)
	v_cndmask_b32_e64 v33, v40, 0, s[66:67]
	v_cndmask_b32_e64 v35, 0, v41, s[68:69]
	v_mul_f32_e32 v37, v37, v33
	v_mul_f32_e32 v39, v39, v35
	v_cvt_pk_bf16_f32 v40, v37, v39
	v_cndmask_b32_e64 v43, v43, 0, s[70:71]
	v_cndmask_b32_e64 v42, v42, 0, s[72:73]
	s_waitcnt lgkmcnt(0)
	v_pk_mul_f32 v[44:45], v[68:69], v[42:43]
	v_and_b32_e32 v39, 0xffff0000, v40
	v_cvt_pk_bf16_f32 v41, v44, v45
	v_lshlrev_b32_e32 v37, 16, v40
	v_mul_f32_e32 v38, v38, v39
	v_fmac_f32_e32 v38, v36, v37
	v_lshlrev_b32_e32 v36, 16, v41
	v_fmac_f32_e32 v38, v32, v36
	v_and_b32_e32 v32, 0xffff0000, v41
	v_fmac_f32_e32 v38, v34, v32
	v_add_f32_e32 v32, v33, v35
	v_add_f32_e32 v33, v42, v43
	v_add_f32_e32 v32, v32, v33
	s_lshl_b32 s81, s81, 8
	ds_write_b64 v157, v[40:41]
	s_waitcnt lgkmcnt(2)
	s_nop 1
	v_add_f32_dpp v33, v38, v38 quad_perm:[1,0,3,2] row_mask:0xf bank_mask:0xf
	s_waitcnt lgkmcnt(1)
	s_nop 1
	v_add_f32_dpp v32, v32, v32 quad_perm:[1,0,3,2] row_mask:0xf bank_mask:0xf
	s_waitcnt lgkmcnt(1)
	s_nop 1
	v_add_f32_dpp v33, v33, v33 quad_perm:[2,3,0,1] row_mask:0xf bank_mask:0xf
	s_waitcnt lgkmcnt(0)
	s_nop 1
	v_add_f32_dpp v32, v32, v32 quad_perm:[2,3,0,1] row_mask:0xf bank_mask:0xf
	s_waitcnt lgkmcnt(1)
	s_nop 1
	v_add_f32_dpp v33, v33, v33 row_half_mirror row_mask:0xf bank_mask:0xf
	s_waitcnt lgkmcnt(0)
	s_nop 1
	v_add_f32_dpp v34, v32, v32 row_half_mirror row_mask:0xf bank_mask:0xf
	s_waitcnt lgkmcnt(1)
	s_nop 1
	v_add_f32_dpp v32, v33, v33 row_mirror row_mask:0xf bank_mask:0xf
	s_waitcnt lgkmcnt(0)
	s_nop 1
	v_add_f32_dpp v33, v34, v34 row_mirror row_mask:0xf bank_mask:0xf
	ds_bpermute_b32 v34, v103, v32
	ds_bpermute_b32 v35, v103, v33
	s_and_saveexec_b64 s[78:79], s[6:7]
	s_cbranch_execz .LBB0_1145
	s_waitcnt lgkmcnt(1)
	v_add_f32_e32 v32, v32, v34
	s_waitcnt lgkmcnt(0)
	v_add_f32_e32 v33, v33, v35
	ds_write_b32 v141, v32
	ds_write_b32 v140, v33
	s_branch .LBB0_1145
